# locality (XCD-aware work mapping): phase_conv fast path maps workgroup i to 16-token block (i%8)*32 + i/8 so the 3 halo rows shared with the preceding block are read through the same XCD's L2
# speedup vs baseline: 1.0068x; 1.0068x over previous
; DI int otid() { int t = threadIdx.x; asm volatile("" : "+v"(t)); return t; }
; DI void phase_conv(const Params& p) {
;     ...
;     for (size_t idx = (size_t)blockIdx.x * 512 + otid(); idx < (size_t)(MTOK / 8) * 256; idx += (size_t)gridDim.x * 512) {
;         const int tok0 = (int)(idx >> 8) * 8, ch = (int)(idx & 255) * 8, t0 = tok0 & (SEQ - 1);
;         float wv[4][8], bs[8];
;         { const f32x4 b0 = *(const f32x4*)(p.in[15] + ch), b1 = *(const f32x4*)(p.in[15] + ch + 4);
; #pragma unroll
;           for (int e = 0; e < 4; ++e) { bs[e] = b0[e]; bs[4 + e] = b1[e]; } }
; #pragma unroll
;         for (int jx = 0; jx < 4; ++jx) { const f32x4 w0 = *(const f32x4*)(p.in[14] + jx * 2048 + ch), w1 = *(const f32x4*)(p.in[14] + jx * 2048 + ch + 4);
; #pragma unroll
;             for (int e = 0; e < 4; ++e) { wv[jx][e] = w0[e]; wv[jx][4 + e] = w1[e]; } }
;         u32x4 raw[11];
; #pragma unroll
;         for (int r = 0; r < 11; ++r) raw[r] = (r >= 3 || t0 > 0) ? *(const u32x4*)(big + (size_t)(tok0 - 3 + r) * 4096 + ch) : (u32x4){0u, 0u, 0u, 0u};
.LBB0_875:
	s_or_b64 exec, exec, s[8:9]
	s_mov_b32 s3, 0
	s_waitcnt lgkmcnt(0)
	v_mov_b32_e32 v0, v181
	s_barrier
	s_lshl_b64 s[8:9], s[2:3], 9
	s_nop 0
	v_ashrrev_i32_e32 v1, 31, v0
	s_waitcnt vmcnt(0)
	v_lshl_add_u64 v[54:55], s[8:9], 0, v[0:1]
	s_mov_b64 s[8:9], 0x80000
	v_cmp_gt_u64_e32 vcc, s[8:9], v[54:55]
	s_and_saveexec_b64 s[16:17], vcc
	s_cbranch_execz .LBB0_884
	s_cmp_eq_u32 s18, 0x100
	s_cbranch_scc0 .Lcv_orig
	s_load_dwordx2 s[42:43], s[0:1], 0xf0
	s_load_dwordx4 s[12:15], s[0:1], 0x70
	v_and_b32_e32 v88, 0xff, v181
	v_lshrrev_b32_e32 v89, 8, v181
	v_lshlrev_b32_e32 v160, 4, v88
	v_lshl_add_u32 v161, v89, 15, v160
	v_lshl_add_u32 v160, v89, 16, v160
	v_lshlrev_b32_e32 v162, 5, v88
	s_nop 0
	v_readfirstlane_b32 s40, v89
	s_and_b32 s46, s2, 7
	s_lshl_b32 s46, s46, 5
	s_lshr_b32 s47, s2, 3
	s_or_b32 s46, s46, s47
	s_or_b32 s40, s40, s46
	s_waitcnt lgkmcnt(0)
	s_lshl_b32 s41, s46, 17
	s_add_u32 s26, s42, 0xbf00000
	s_addc_u32 s27, s43, 0
	s_add_u32 s26, s26, s41
	s_addc_u32 s27, s27, 0
	s_sub_u32 s26, s26, 0x6000
	s_subb_u32 s27, s27, 0
	s_lshl_b32 s41, s46, 16
	s_add_u32 s28, s42, 0x7f00000
	s_addc_u32 s29, s43, 0
	s_add_u32 s28, s28, s41
	s_addc_u32 s29, s29, 0
	s_mov_b64 s[44:45], s[12:13]
	global_load_dwordx4 v[232:235], v162, s[44:45]
	global_load_dwordx4 v[236:239], v162, s[44:45] offset:16
	s_add_u32 s44, s44, 0x2000
	s_addc_u32 s45, s45, 0
	global_load_dwordx4 v[240:243], v162, s[44:45]
	global_load_dwordx4 v[244:247], v162, s[44:45] offset:16
	s_add_u32 s44, s44, 0x2000
	s_addc_u32 s45, s45, 0
	global_load_dwordx4 v[248:251], v162, s[44:45]
	global_load_dwordx4 v[252:255], v162, s[44:45] offset:16
	s_add_u32 s44, s44, 0x2000
	s_addc_u32 s45, s45, 0
	global_load_dwordx4 v[198:201], v162, s[44:45]
	global_load_dwordx4 v[202:205], v162, s[44:45] offset:16
	global_load_dwordx4 v[206:209], v162, s[14:15]
	global_load_dwordx4 v[210:213], v162, s[14:15] offset:16
	s_mov_b64 s[44:45], s[26:27]
	global_load_dwordx4 v[0:3], v160, s[44:45]
	s_add_u32 s44, s44, 0x2000
	s_addc_u32 s45, s45, 0
	global_load_dwordx4 v[4:7], v160, s[44:45]
	s_add_u32 s44, s44, 0x2000
	s_addc_u32 s45, s45, 0
	global_load_dwordx4 v[8:11], v160, s[44:45]
	s_add_u32 s44, s44, 0x2000
	s_addc_u32 s45, s45, 0
	global_load_dwordx4 v[12:15], v160, s[44:45]
	s_add_u32 s44, s44, 0x2000
	s_addc_u32 s45, s45, 0
	global_load_dwordx4 v[16:19], v160, s[44:45]
	s_add_u32 s44, s44, 0x2000
	s_addc_u32 s45, s45, 0
	global_load_dwordx4 v[20:23], v160, s[44:45]
	s_add_u32 s44, s44, 0x2000
	s_addc_u32 s45, s45, 0
	global_load_dwordx4 v[24:27], v160, s[44:45]
	s_add_u32 s44, s44, 0x2000
	s_addc_u32 s45, s45, 0
	global_load_dwordx4 v[28:31], v160, s[44:45]
	s_add_u32 s44, s44, 0x2000
	s_addc_u32 s45, s45, 0
	global_load_dwordx4 v[32:35], v160, s[44:45]
	s_add_u32 s44, s44, 0x2000
	s_addc_u32 s45, s45, 0
	global_load_dwordx4 v[36:39], v160, s[44:45]
	s_add_u32 s44, s44, 0x2000
	s_addc_u32 s45, s45, 0
	global_load_dwordx4 v[40:43], v160, s[44:45]
	s_add_u32 s26, s26, 0x2000000
	s_addc_u32 s27, s27, 0
	s_mov_b64 s[44:45], s[26:27]
	global_load_dwordx4 v[44:47], v160, s[44:45]
	s_add_u32 s44, s44, 0x2000
	s_addc_u32 s45, s45, 0
	global_load_dwordx4 v[48:51], v160, s[44:45]
	s_add_u32 s44, s44, 0x2000
	s_addc_u32 s45, s45, 0
	global_load_dwordx4 v[52:55], v160, s[44:45]
	s_add_u32 s44, s44, 0x2000
	s_addc_u32 s45, s45, 0
	global_load_dwordx4 v[56:59], v160, s[44:45]
	s_add_u32 s44, s44, 0x2000
	s_addc_u32 s45, s45, 0
	global_load_dwordx4 v[60:63], v160, s[44:45]
	s_add_u32 s44, s44, 0x2000
	s_addc_u32 s45, s45, 0
	global_load_dwordx4 v[64:67], v160, s[44:45]
	s_add_u32 s44, s44, 0x2000
	s_addc_u32 s45, s45, 0
	global_load_dwordx4 v[68:71], v160, s[44:45]
	s_add_u32 s44, s44, 0x2000
	s_addc_u32 s45, s45, 0
	global_load_dwordx4 v[72:75], v160, s[44:45]
	s_add_u32 s44, s44, 0x2000
	s_addc_u32 s45, s45, 0
	global_load_dwordx4 v[76:79], v160, s[44:45]
	s_add_u32 s44, s44, 0x2000
	s_addc_u32 s45, s45, 0
	global_load_dwordx4 v[80:83], v160, s[44:45]
	s_add_u32 s44, s44, 0x2000
	s_addc_u32 s45, s45, 0
	global_load_dwordx4 v[84:87], v160, s[44:45]
	s_add_u32 s26, s26, 0x2000000
	s_addc_u32 s27, s27, 0
	s_waitcnt vmcnt(11)
	s_cmp_eq_u32 s40, 0
	s_cbranch_scc0 .Lcv_nopad0
	v_mov_b32_e32 v0, 0
	v_mov_b32_e32 v1, 0
	v_mov_b32_e32 v2, 0
	v_mov_b32_e32 v3, 0
	v_mov_b32_e32 v4, 0
	v_mov_b32_e32 v5, 0
	v_mov_b32_e32 v6, 0
	v_mov_b32_e32 v7, 0
	v_mov_b32_e32 v8, 0
	v_mov_b32_e32 v9, 0
	v_mov_b32_e32 v10, 0
	v_mov_b32_e32 v11, 0
